# FoX unmasked tiles: p0 accumulation chain first so p0's exps issue under p1's MFMAs; V fragments fetched into released K-fragment registers
# baseline (speedup 1.0000x reference)
; #define LAS3 __attribute__((address_space(3)))
; __device__ __forceinline__ void fox_unit(int b, int hh, int qb, const bf16_t* Q, const bf16_t* __restrict__ K, const bf16_t* __restrict__ V, bf16_t* O, ...
;     ...
;         if (64 * jt <= qw0 + 31 && (excess || jp >= jp_lastw)) {
;             const LAS3 unsigned char* kp = kp0 + slot * SLOTB; const LAS3 unsigned char* fp = fp0 + slot * 1024;
;             asm volatile("" : "+v"(cinit));
;             f32x16 p0 = __builtin_amdgcn_mfma_f32_32x32x16_bf16(*(const LAS3 bf16x8*)(fp), qones, cinit, 0, 0, 0);
;             f32x16 p1 = __builtin_amdgcn_mfma_f32_32x32x16_bf16(*(const LAS3 bf16x8*)(fp + 512), qones, cinit, 0, 0, 0);
; #pragma unroll
;             for (int d0 = 0; d0 < 4; ++d0) {
;                 const bf16x8 k0 = *(const LAS3 bf16x8*)(kp + d0 * 2048), k1 = *(const LAS3 bf16x8*)(kp + d0 * 2048 + 512);
;                 p0 = __builtin_amdgcn_mfma_f32_32x32x16_bf16(k0, qr[d0], p0, 0, 0, 0);
;                 p1 = __builtin_amdgcn_mfma_f32_32x32x16_bf16(k1, qr[d0], p1, 0, 0, 0);
;             }
.LBB0_427:
	s_cmp_ge_i32 s3, s74
	s_cselect_b64 s[12:13], -1, 0
	s_or_b64 s[94:95], s[84:85], s[12:13]
	s_add_i32 s12, s96, s71
	s_add_i32 s7, s12, 0x1fc0
	s_cmp_le_u32 s7, s33
	s_cselect_b64 s[14:15], -1, 0
	s_and_b64 s[14:15], s[14:15], s[94:95]
	s_andn2_b64 vcc, exec, s[14:15]
	s_cbranch_vccnz .LBB0_431
	s_add_i32 s7, s6, -1
	s_and_b32 s7, s7, 3
	v_lshl_add_u32 v2, s7, 10, v166
	ds_read_b128 v[188:191], v2
	ds_read_b128 v[192:195], v2 offset:512
	s_lshl_b32 s7, s7, 13
	v_add_u32_e32 v2, s7, v137
	ds_read_b128 v[196:199], v2
	ds_read_b128 v[200:203], v2 offset:512
	ds_read_b128 v[204:207], v2 offset:2048
	ds_read_b128 v[208:211], v2 offset:2560
	ds_read_b128 v[212:215], v2 offset:4096
	ds_read_b128 v[216:219], v2 offset:4608
	ds_read_b128 v[220:223], v2 offset:6144
	ds_read_b128 v[224:227], v2 offset:6656
	s_addk_i32 s12, 0x1fff
	s_cmp_le_u32 s12, s70
	v_add_u32_e32 v186, s7, v165
	s_cbranch_scc1 .Lfox_fast1
	s_waitcnt lgkmcnt(9)
	v_mfma_f32_32x32x16_bf16 v[82:97], v[188:191], v[114:117], v[50:65]
	s_waitcnt lgkmcnt(8)
	v_mfma_f32_32x32x16_bf16 v[98:113], v[192:195], v[114:117], v[50:65]
	s_waitcnt lgkmcnt(7)
	v_mfma_f32_32x32x16_bf16 v[82:97], v[196:199], v[118:121], v[82:97]
	s_waitcnt lgkmcnt(6)
	v_mfma_f32_32x32x16_bf16 v[98:113], v[200:203], v[118:121], v[98:113]
	s_waitcnt lgkmcnt(5)
	v_mfma_f32_32x32x16_bf16 v[82:97], v[204:207], v[122:125], v[82:97]
	s_waitcnt lgkmcnt(4)
	v_mfma_f32_32x32x16_bf16 v[98:113], v[208:211], v[122:125], v[98:113]
	s_waitcnt lgkmcnt(3)
	v_mfma_f32_32x32x16_bf16 v[82:97], v[212:215], v[126:129], v[82:97]
	s_waitcnt lgkmcnt(2)
	v_mfma_f32_32x32x16_bf16 v[98:113], v[216:219], v[126:129], v[98:113]
	s_waitcnt lgkmcnt(1)
	v_mfma_f32_32x32x16_bf16 v[82:97], v[220:223], v[130:133], v[82:97]
	s_waitcnt lgkmcnt(0)
	v_mfma_f32_32x32x16_bf16 v[98:113], v[224:227], v[130:133], v[98:113]
	ds_read_b64_tr_b16 v[188:189], v186 offset:32768
	ds_read_b64_tr_b16 v[190:191], v186 offset:33280
	ds_read_b64_tr_b16 v[192:193], v186 offset:36864
	ds_read_b64_tr_b16 v[194:195], v186 offset:37376
	ds_read_b64_tr_b16 v[196:197], v186 offset:33792
	ds_read_b64_tr_b16 v[198:199], v186 offset:34304
	ds_read_b64_tr_b16 v[200:201], v186 offset:37888
	ds_read_b64_tr_b16 v[202:203], v186 offset:38400
	ds_read_b64_tr_b16 v[204:205], v186 offset:34816
	ds_read_b64_tr_b16 v[206:207], v186 offset:35328
	ds_read_b64_tr_b16 v[208:209], v186 offset:38912
	ds_read_b64_tr_b16 v[210:211], v186 offset:39424
	ds_read_b64_tr_b16 v[212:213], v186 offset:35840
	ds_read_b64_tr_b16 v[214:215], v186 offset:36352
	ds_read_b64_tr_b16 v[216:217], v186 offset:39936
	ds_read_b64_tr_b16 v[218:219], v186 offset:40448
	s_cbranch_scc1 .LBB0_430
; __device__ __forceinline__ void fox_unit(int b, int hh, int qb, const bf16_t* Q, const bf16_t* __restrict__ K, const bf16_t* __restrict__ V, bf16_t* O, ...
;     ...
;             if (64 * jt + 63 > qw0) { const int kb_ = 64 * jt + 4 * hi - (qw0 + r32);
; #pragma unroll
;                 for (int r = 0; r < 16; ++r) { const int cr = (r & 3) + 8 * (r >> 2); if (kb_ + cr > 0) p0[r] = -INFINITY; if (kb_ + cr + 32 > 0) p1[r] = -INFINITY; } }
	v_add_u32_e32 v2, s71, v155
	v_add_u32_e32 v2, 0xc0, v2
	s_movk_i32 s40, 0xffe6
	s_movk_i32 s68, 0xffe5
	s_movk_i32 s38, 0xffe7
	v_cmp_lt_i32_e64 s[66:67], s40, v2
	v_cmp_lt_i32_e64 s[68:69], s68, v2
	s_movk_i32 s36, 0xffe8
	v_cmp_lt_i32_e64 s[64:65], s38, v2
	s_and_b64 s[66:67], s[68:69], s[66:67]
	s_movk_i32 s34, 0xffed
	v_cmp_lt_i32_e64 s[62:63], s36, v2
	s_and_b64 s[64:65], s[66:67], s[64:65]
	s_movk_i32 s30, 0xffee
	v_cmp_lt_i32_e64 s[60:61], s34, v2
	s_and_b64 s[62:63], s[64:65], s[62:63]
	s_movk_i32 s28, 0xffef
	v_cmp_lt_i32_e64 s[58:59], s30, v2
	s_and_b64 s[60:61], s[62:63], s[60:61]
	v_cmp_lt_i32_e64 s[56:57], s28, v2
	s_and_b64 s[58:59], s[60:61], s[58:59]
	v_cmp_lt_i32_e64 s[54:55], -16, v2
	s_and_b64 s[56:57], s[58:59], s[56:57]
	v_cmp_lt_i32_e64 s[52:53], -11, v2
	s_and_b64 s[54:55], s[56:57], s[54:55]
	v_cmp_lt_i32_e64 s[50:51], -10, v2
	s_and_b64 s[52:53], s[54:55], s[52:53]
	v_cmp_lt_i32_e64 s[48:49], -9, v2
	s_and_b64 s[50:51], s[52:53], s[50:51]
	s_movk_i32 s14, 0xffe0
	v_cmp_lt_i32_e64 s[46:47], -8, v2
	s_and_b64 s[48:49], s[50:51], s[48:49]
	v_cmp_gt_i32_e64 s[12:13], 1, v2
	v_cmp_lt_i32_e32 vcc, s14, v2
	v_cmp_gt_i32_e64 s[14:15], 0, v2
	v_cmp_lt_i32_e64 s[44:45], -3, v2
	s_and_b64 s[46:47], s[48:49], s[46:47]
	s_or_b64 s[12:13], s[14:15], s[12:13]
	v_cmp_lt_i32_e64 s[42:43], -2, v2
	s_and_b64 s[44:45], s[46:47], s[44:45]
	v_cndmask_b32_e64 v4, v174, v83, s[14:15]
	v_cndmask_b32_e64 v5, v174, v82, s[12:13]
	s_and_b64 s[42:43], s[44:45], s[42:43]
	s_movk_i32 s40, 0xffc6
	v_cndmask_b32_e64 v82, v82, v5, s[42:43]
	v_cndmask_b32_e64 v84, v84, v174, s[42:43]
	v_cndmask_b32_e64 v83, v83, v4, s[42:43]
	s_movk_i32 s42, 0xffc5
	s_movk_i32 s38, 0xffc7
	v_cmp_lt_i32_e64 s[40:41], s40, v2
	v_cmp_lt_i32_e64 s[42:43], s42, v2
	s_movk_i32 s36, 0xffc8
	v_cmp_lt_i32_e64 s[38:39], s38, v2
	s_and_b64 s[40:41], s[42:43], s[40:41]
	s_movk_i32 s34, 0xffcd
	v_cmp_lt_i32_e64 s[36:37], s36, v2
	s_and_b64 s[38:39], s[40:41], s[38:39]
	s_movk_i32 s30, 0xffce
	v_cmp_lt_i32_e64 s[34:35], s34, v2
	s_and_b64 s[36:37], s[38:39], s[36:37]
	s_movk_i32 s28, 0xffcf
	v_cmp_lt_i32_e64 s[30:31], s30, v2
	s_and_b64 s[34:35], s[36:37], s[34:35]
	s_movk_i32 s26, 0xffd0
	v_cmp_lt_i32_e64 s[28:29], s28, v2
	s_and_b64 s[30:31], s[34:35], s[30:31]
	s_movk_i32 s24, 0xffd5
	v_cmp_lt_i32_e64 s[26:27], s26, v2
	s_and_b64 s[28:29], s[30:31], s[28:29]
	s_movk_i32 s22, 0xffd6
	v_cmp_lt_i32_e64 s[24:25], s24, v2
	s_and_b64 s[26:27], s[28:29], s[26:27]
	s_movk_i32 s20, 0xffd7
	v_cmp_lt_i32_e64 s[22:23], s22, v2
	s_and_b64 s[24:25], s[26:27], s[24:25]
	s_movk_i32 s18, 0xffd8
	v_cmp_lt_i32_e64 s[20:21], s20, v2
	s_and_b64 s[22:23], s[24:25], s[22:23]
	s_movk_i32 s16, 0xffdd
	v_cmp_lt_i32_e64 s[18:19], s18, v2
	s_and_b64 s[20:21], s[22:23], s[20:21]
	s_movk_i32 s14, 0xffde
	v_cmp_lt_i32_e64 s[16:17], s16, v2
	s_and_b64 s[18:19], s[20:21], s[18:19]
	s_movk_i32 s12, 0xffdf
	v_cmp_lt_i32_e64 s[14:15], s14, v2
	s_and_b64 s[16:17], s[18:19], s[16:17]
	v_cmp_lt_i32_e64 s[12:13], s12, v2
	s_and_b64 s[14:15], s[16:17], s[14:15]
	s_and_b64 s[12:13], s[14:15], s[12:13]
	s_and_b64 vcc, s[12:13], vcc
	v_cndmask_b32_e64 v97, v97, v174, s[68:69]
	v_cndmask_b32_e64 v96, v96, v174, s[66:67]
	v_cndmask_b32_e64 v95, v95, v174, s[64:65]
	v_cndmask_b32_e64 v94, v94, v174, s[62:63]
	v_cndmask_b32_e64 v93, v93, v174, s[60:61]
	v_cndmask_b32_e64 v92, v92, v174, s[58:59]
	v_cndmask_b32_e64 v91, v91, v174, s[56:57]
	v_cndmask_b32_e64 v90, v90, v174, s[54:55]
	v_cndmask_b32_e64 v89, v89, v174, s[52:53]
	v_cndmask_b32_e64 v88, v88, v174, s[50:51]
	v_cndmask_b32_e64 v87, v87, v174, s[48:49]
	v_cndmask_b32_e64 v86, v86, v174, s[46:47]
	v_cndmask_b32_e64 v85, v85, v174, s[44:45]
	v_cndmask_b32_e64 v113, v113, v174, s[42:43]
	v_cndmask_b32_e64 v112, v112, v174, s[40:41]
	v_cndmask_b32_e64 v111, v111, v174, s[38:39]
	v_cndmask_b32_e64 v110, v110, v174, s[36:37]
	v_cndmask_b32_e64 v109, v109, v174, s[34:35]
	v_cndmask_b32_e64 v108, v108, v174, s[30:31]
	v_cndmask_b32_e64 v107, v107, v174, s[28:29]
	v_cndmask_b32_e64 v106, v106, v174, s[26:27]
	v_cndmask_b32_e64 v105, v105, v174, s[24:25]
	v_cndmask_b32_e64 v104, v104, v174, s[22:23]
	v_cndmask_b32_e64 v103, v103, v174, s[20:21]
	v_cndmask_b32_e64 v102, v102, v174, s[18:19]
	v_cndmask_b32_e64 v101, v101, v174, s[16:17]
	v_cndmask_b32_e64 v100, v100, v174, s[14:15]
	v_cndmask_b32_e64 v99, v99, v174, s[12:13]
	v_cndmask_b32_e32 v98, v98, v174, vcc

; #define LAS3 __attribute__((address_space(3)))
; __device__ __forceinline__ void fox_unit(int b, int hh, int qb, const bf16_t* Q, const bf16_t* __restrict__ K, const bf16_t* __restrict__ V, bf16_t* O, ...
;     ...
;         if (64 * jt <= qw0 + 31 && (excess || jp >= jp_lastw)) {
;             const LAS3 unsigned char* kp = kp0 + slot * SLOTB; const LAS3 unsigned char* fp = fp0 + slot * 1024;
;             asm volatile("" : "+v"(cinit));
;             f32x16 p0 = __builtin_amdgcn_mfma_f32_32x32x16_bf16(*(const LAS3 bf16x8*)(fp), qones, cinit, 0, 0, 0);
;             f32x16 p1 = __builtin_amdgcn_mfma_f32_32x32x16_bf16(*(const LAS3 bf16x8*)(fp + 512), qones, cinit, 0, 0, 0);
; #pragma unroll
;             for (int d0 = 0; d0 < 4; ++d0) {
;                 const bf16x8 k0 = *(const LAS3 bf16x8*)(kp + d0 * 2048), k1 = *(const LAS3 bf16x8*)(kp + d0 * 2048 + 512);
;                 p0 = __builtin_amdgcn_mfma_f32_32x32x16_bf16(k0, qr[d0], p0, 0, 0, 0);
;                 p1 = __builtin_amdgcn_mfma_f32_32x32x16_bf16(k1, qr[d0], p1, 0, 0, 0);
;             }
;             if (64 * jt + 63 > qw0) { const int kb_ = 64 * jt + 4 * hi - (qw0 + r32);
; #pragma unroll
;                 for (int r = 0; r < 16; ++r) { const int cr = (r & 3) + 8 * (r >> 2); if (kb_ + cr > 0) p0[r] = -INFINITY; if (kb_ + cr + 32 > 0) p1[r] = -INFINITY; } }
.LBB0_431:
	s_add_i32 s12, s2, s71
	s_add_i32 s7, s12, 0xffffff80
	s_cmp_le_u32 s7, s33
	s_cselect_b64 s[14:15], -1, 0
	s_and_b64 s[14:15], s[14:15], s[94:95]
	s_andn2_b64 vcc, exec, s[14:15]
	s_cbranch_vccnz .LBB0_435
	s_add_i32 s7, s6, 2
	s_and_b32 s7, s7, 2
	v_lshl_add_u32 v2, s7, 10, v166
	ds_read_b128 v[188:191], v2
	ds_read_b128 v[192:195], v2 offset:512
	s_lshl_b32 s7, s7, 13
	v_add_u32_e32 v2, s7, v137
	ds_read_b128 v[196:199], v2
	ds_read_b128 v[200:203], v2 offset:512
	ds_read_b128 v[204:207], v2 offset:2048
	ds_read_b128 v[208:211], v2 offset:2560
	ds_read_b128 v[212:215], v2 offset:4096
	ds_read_b128 v[216:219], v2 offset:4608
	ds_read_b128 v[220:223], v2 offset:6144
	ds_read_b128 v[224:227], v2 offset:6656
	s_addk_i32 s12, 0xffbf
	s_cmp_le_u32 s12, s70
	v_add_u32_e32 v186, s7, v165
	s_cbranch_scc1 .Lfox_fast2
	s_waitcnt lgkmcnt(9)
	v_mfma_f32_32x32x16_bf16 v[82:97], v[188:191], v[114:117], v[50:65]
	s_waitcnt lgkmcnt(8)
	v_mfma_f32_32x32x16_bf16 v[98:113], v[192:195], v[114:117], v[50:65]
	s_waitcnt lgkmcnt(7)
	v_mfma_f32_32x32x16_bf16 v[82:97], v[196:199], v[118:121], v[82:97]
	s_waitcnt lgkmcnt(6)
	v_mfma_f32_32x32x16_bf16 v[98:113], v[200:203], v[118:121], v[98:113]
	s_waitcnt lgkmcnt(5)
	v_mfma_f32_32x32x16_bf16 v[82:97], v[204:207], v[122:125], v[82:97]
	s_waitcnt lgkmcnt(4)
	v_mfma_f32_32x32x16_bf16 v[98:113], v[208:211], v[122:125], v[98:113]
	s_waitcnt lgkmcnt(3)
	v_mfma_f32_32x32x16_bf16 v[82:97], v[212:215], v[126:129], v[82:97]
	s_waitcnt lgkmcnt(2)
	v_mfma_f32_32x32x16_bf16 v[98:113], v[216:219], v[126:129], v[98:113]
	s_waitcnt lgkmcnt(1)
	v_mfma_f32_32x32x16_bf16 v[82:97], v[220:223], v[130:133], v[82:97]
	s_waitcnt lgkmcnt(0)
	v_mfma_f32_32x32x16_bf16 v[98:113], v[224:227], v[130:133], v[98:113]
	ds_read_b64_tr_b16 v[188:189], v186 offset:32768
	ds_read_b64_tr_b16 v[190:191], v186 offset:33280
	ds_read_b64_tr_b16 v[192:193], v186 offset:36864
	ds_read_b64_tr_b16 v[194:195], v186 offset:37376
	ds_read_b64_tr_b16 v[196:197], v186 offset:33792
	ds_read_b64_tr_b16 v[198:199], v186 offset:34304
	ds_read_b64_tr_b16 v[200:201], v186 offset:37888
	ds_read_b64_tr_b16 v[202:203], v186 offset:38400
	ds_read_b64_tr_b16 v[204:205], v186 offset:34816
	ds_read_b64_tr_b16 v[206:207], v186 offset:35328
	ds_read_b64_tr_b16 v[208:209], v186 offset:38912
	ds_read_b64_tr_b16 v[210:211], v186 offset:39424
	ds_read_b64_tr_b16 v[212:213], v186 offset:35840
	ds_read_b64_tr_b16 v[214:215], v186 offset:36352
	ds_read_b64_tr_b16 v[216:217], v186 offset:39936
	ds_read_b64_tr_b16 v[218:219], v186 offset:40448
	s_cbranch_scc1 .LBB0_434
	v_add_u32_e32 v2, s71, v153
	s_movk_i32 s40, 0xffe6
	s_movk_i32 s68, 0xffe5
	s_movk_i32 s38, 0xffe7
	v_cmp_lt_i32_e64 s[66:67], s40, v2
	v_cmp_lt_i32_e64 s[68:69], s68, v2
	s_movk_i32 s36, 0xffe8
	v_cmp_lt_i32_e64 s[64:65], s38, v2
	s_and_b64 s[66:67], s[68:69], s[66:67]
	s_movk_i32 s34, 0xffed
	v_cmp_lt_i32_e64 s[62:63], s36, v2
	s_and_b64 s[64:65], s[66:67], s[64:65]
	s_movk_i32 s30, 0xffee
	v_cmp_lt_i32_e64 s[60:61], s34, v2
	s_and_b64 s[62:63], s[64:65], s[62:63]
	s_movk_i32 s28, 0xffef
	v_cmp_lt_i32_e64 s[58:59], s30, v2
	s_and_b64 s[60:61], s[62:63], s[60:61]
	v_cmp_lt_i32_e64 s[56:57], s28, v2
	s_and_b64 s[58:59], s[60:61], s[58:59]
	v_cmp_lt_i32_e64 s[54:55], -16, v2
	s_and_b64 s[56:57], s[58:59], s[56:57]
	v_cmp_lt_i32_e64 s[52:53], -11, v2
	s_and_b64 s[54:55], s[56:57], s[54:55]
	v_cmp_lt_i32_e64 s[50:51], -10, v2
	s_and_b64 s[52:53], s[54:55], s[52:53]
	v_cmp_lt_i32_e64 s[48:49], -9, v2
	s_and_b64 s[50:51], s[52:53], s[50:51]
	s_movk_i32 s14, 0xffe0
	v_cmp_lt_i32_e64 s[46:47], -8, v2
	s_and_b64 s[48:49], s[50:51], s[48:49]
	v_cmp_gt_i32_e64 s[12:13], 1, v2
	v_cmp_lt_i32_e32 vcc, s14, v2
	v_cmp_gt_i32_e64 s[14:15], 0, v2
	v_cmp_lt_i32_e64 s[44:45], -3, v2
	s_and_b64 s[46:47], s[48:49], s[46:47]
	s_or_b64 s[12:13], s[14:15], s[12:13]
	v_cmp_lt_i32_e64 s[42:43], -2, v2
	s_and_b64 s[44:45], s[46:47], s[44:45]
	v_cndmask_b32_e64 v4, v174, v83, s[14:15]
	v_cndmask_b32_e64 v5, v174, v82, s[12:13]
	s_and_b64 s[42:43], s[44:45], s[42:43]
	s_movk_i32 s40, 0xffc6
	v_cndmask_b32_e64 v82, v82, v5, s[42:43]
	v_cndmask_b32_e64 v84, v84, v174, s[42:43]
	v_cndmask_b32_e64 v83, v83, v4, s[42:43]
	s_movk_i32 s42, 0xffc5
	s_movk_i32 s38, 0xffc7
	v_cmp_lt_i32_e64 s[40:41], s40, v2
	v_cmp_lt_i32_e64 s[42:43], s42, v2
	s_movk_i32 s36, 0xffc8
	v_cmp_lt_i32_e64 s[38:39], s38, v2
	s_and_b64 s[40:41], s[42:43], s[40:41]
	s_movk_i32 s34, 0xffcd
	v_cmp_lt_i32_e64 s[36:37], s36, v2
	s_and_b64 s[38:39], s[40:41], s[38:39]
	s_movk_i32 s30, 0xffce
	v_cmp_lt_i32_e64 s[34:35], s34, v2
	s_and_b64 s[36:37], s[38:39], s[36:37]
	s_movk_i32 s28, 0xffcf
	v_cmp_lt_i32_e64 s[30:31], s30, v2
	s_and_b64 s[34:35], s[36:37], s[34:35]
	s_movk_i32 s26, 0xffd0
	v_cmp_lt_i32_e64 s[28:29], s28, v2
	s_and_b64 s[30:31], s[34:35], s[30:31]
	s_movk_i32 s24, 0xffd5
	v_cmp_lt_i32_e64 s[26:27], s26, v2
	s_and_b64 s[28:29], s[30:31], s[28:29]
	s_movk_i32 s22, 0xffd6
	v_cmp_lt_i32_e64 s[24:25], s24, v2
	s_and_b64 s[26:27], s[28:29], s[26:27]
	s_movk_i32 s20, 0xffd7
	v_cmp_lt_i32_e64 s[22:23], s22, v2
	s_and_b64 s[24:25], s[26:27], s[24:25]
	s_movk_i32 s18, 0xffd8
	v_cmp_lt_i32_e64 s[20:21], s20, v2
	s_and_b64 s[22:23], s[24:25], s[22:23]
	s_movk_i32 s16, 0xffdd
	v_cmp_lt_i32_e64 s[18:19], s18, v2
	s_and_b64 s[20:21], s[22:23], s[20:21]
	s_movk_i32 s14, 0xffde
	v_cmp_lt_i32_e64 s[16:17], s16, v2
	s_and_b64 s[18:19], s[20:21], s[18:19]
	s_movk_i32 s12, 0xffdf
	v_cmp_lt_i32_e64 s[14:15], s14, v2
	s_and_b64 s[16:17], s[18:19], s[16:17]
	v_cmp_lt_i32_e64 s[12:13], s12, v2
	s_and_b64 s[14:15], s[16:17], s[14:15]
	s_and_b64 s[12:13], s[14:15], s[12:13]
	s_and_b64 vcc, s[12:13], vcc
	v_cndmask_b32_e64 v97, v97, v174, s[68:69]
	v_cndmask_b32_e64 v96, v96, v174, s[66:67]
	v_cndmask_b32_e64 v95, v95, v174, s[64:65]
	v_cndmask_b32_e64 v94, v94, v174, s[62:63]
	v_cndmask_b32_e64 v93, v93, v174, s[60:61]
	v_cndmask_b32_e64 v92, v92, v174, s[58:59]
	v_cndmask_b32_e64 v91, v91, v174, s[56:57]
	v_cndmask_b32_e64 v90, v90, v174, s[54:55]
	v_cndmask_b32_e64 v89, v89, v174, s[52:53]
	v_cndmask_b32_e64 v88, v88, v174, s[50:51]
	v_cndmask_b32_e64 v87, v87, v174, s[48:49]
	v_cndmask_b32_e64 v86, v86, v174, s[46:47]
	v_cndmask_b32_e64 v85, v85, v174, s[44:45]
	v_cndmask_b32_e64 v113, v113, v174, s[42:43]
	v_cndmask_b32_e64 v112, v112, v174, s[40:41]
	v_cndmask_b32_e64 v111, v111, v174, s[38:39]
	v_cndmask_b32_e64 v110, v110, v174, s[36:37]
	v_cndmask_b32_e64 v109, v109, v174, s[34:35]
	v_cndmask_b32_e64 v108, v108, v174, s[30:31]
	v_cndmask_b32_e64 v107, v107, v174, s[28:29]
	v_cndmask_b32_e64 v106, v106, v174, s[26:27]
	v_cndmask_b32_e64 v105, v105, v174, s[24:25]
	v_cndmask_b32_e64 v104, v104, v174, s[22:23]
	v_cndmask_b32_e64 v103, v103, v174, s[20:21]
	v_cndmask_b32_e64 v102, v102, v174, s[18:19]
	v_cndmask_b32_e64 v101, v101, v174, s[16:17]
	v_cndmask_b32_e64 v100, v100, v174, s[14:15]
	v_cndmask_b32_e64 v99, v99, v174, s[12:13]
	v_cndmask_b32_e32 v98, v98, v174, vcc

; #define LAS3 __attribute__((address_space(3)))
; __device__ __forceinline__ void fox_unit(int b, int hh, int qb, const bf16_t* Q, const bf16_t* __restrict__ K, const bf16_t* __restrict__ V, bf16_t* O, ...
;     ...
;             f32x16 p0 = __builtin_amdgcn_mfma_f32_32x32x16_bf16(*(const LAS3 bf16x8*)(fp), qones, cinit, 0, 0, 0);
;             f32x16 p1 = __builtin_amdgcn_mfma_f32_32x32x16_bf16(*(const LAS3 bf16x8*)(fp + 512), qones, cinit, 0, 0, 0);
; #pragma unroll
;             for (int d0 = 0; d0 < 4; ++d0) {
;                 const bf16x8 k0 = *(const LAS3 bf16x8*)(kp + d0 * 2048), k1 = *(const LAS3 bf16x8*)(kp + d0 * 2048 + 512);
;                 p0 = __builtin_amdgcn_mfma_f32_32x32x16_bf16(k0, qr[d0], p0, 0, 0, 0);
;                 p1 = __builtin_amdgcn_mfma_f32_32x32x16_bf16(k1, qr[d0], p1, 0, 0, 0);
;             }
;             if (64 * jt + 63 > qw0) { const int kb_ = 64 * jt + 4 * hi - (qw0 + r32);
; #pragma unroll
;                 for (int r = 0; r < 16; ++r) { const int cr = (r & 3) + 8 * (r >> 2); if (kb_ + cr > 0) p0[r] = -INFINITY; if (kb_ + cr + 32 > 0) p1[r] = -INFINITY; } }
; #pragma unroll
;             for (int r = 0; r < 16; ++r) { p0[r] = __builtin_amdgcn_exp2f(p0[r]); p1[r] = __builtin_amdgcn_exp2f(p1[r]); }
;             u32x4 pw[4];
; #pragma unroll
;             for (int i = 0; i < 4; ++i) { pw[0][i] = cvtpk(p0[2 * i], p0[2 * i + 1]); pw[1][i] = cvtpk(p0[8 + 2 * i], p0[8 + 2 * i + 1]); pw[2][i] = cvtpk(p1[2 * i], p1[2 * i + 1]); pw[3][i] = cvtpk(p1[8 + 2 * i], p1[8 + 2 * i + 1]); }
;             const LAS3 unsigned char* vp = vp0 + slot * SLOTB;
; #pragma unroll
;             for (int ks = 0; ks < 4; ++ks) {
;                 const s16x4 l0 = vtr(vp + ks * 1024), h0 = vtr(vp + ks * 1024 + 512), l1 = vtr(vp + 4096 + ks * 1024), h1 = vtr(vp + 4096 + ks * 1024 + 512);
;                 const bf16x8 v0 = (bf16x8){l0[0], l0[1], l0[2], l0[3], h0[0], h0[1], h0[2], h0[3]}, v1 = (bf16x8){l1[0], l1[1], l1[2], l1[3], h1[0], h1[1], h1[2], h1[3]};
;                 const bf16x8 pf = __builtin_bit_cast(bf16x8, pw[ks]);
;                 o0 = __builtin_amdgcn_mfma_f32_32x32x16_bf16(v0, pf, o0, 0, 0, 0);
;                 o1 = __builtin_amdgcn_mfma_f32_32x32x16_bf16(v1, pf, o1, 0, 0, 0);
;                 lacc = __builtin_amdgcn_mfma_f32_32x32x16_bf16(onesA, pf, lacc, 0, 0, 0);
;             }
.Lfox_fast1:
	s_waitcnt lgkmcnt(9)
	v_mfma_f32_32x32x16_bf16 v[82:97], v[188:191], v[114:117], v[50:65]
	s_waitcnt lgkmcnt(7)
	v_mfma_f32_32x32x16_bf16 v[82:97], v[196:199], v[118:121], v[82:97]
	s_waitcnt lgkmcnt(5)
	v_mfma_f32_32x32x16_bf16 v[82:97], v[204:207], v[122:125], v[82:97]
	s_waitcnt lgkmcnt(3)
	v_mfma_f32_32x32x16_bf16 v[82:97], v[212:215], v[126:129], v[82:97]
	s_waitcnt lgkmcnt(1)
	v_mfma_f32_32x32x16_bf16 v[82:97], v[220:223], v[130:133], v[82:97]
	s_waitcnt lgkmcnt(0)
	v_mfma_f32_32x32x16_bf16 v[98:113], v[192:195], v[114:117], v[50:65]
	ds_read_b64_tr_b16 v[188:189], v186 offset:32768
	ds_read_b64_tr_b16 v[190:191], v186 offset:33280
	ds_read_b64_tr_b16 v[196:197], v186 offset:36864
	ds_read_b64_tr_b16 v[198:199], v186 offset:37376
	v_mfma_f32_32x32x16_bf16 v[98:113], v[200:203], v[118:121], v[98:113]
	ds_read_b64_tr_b16 v[204:205], v186 offset:33792
	ds_read_b64_tr_b16 v[206:207], v186 offset:34304
	ds_read_b64_tr_b16 v[212:213], v186 offset:37888
	ds_read_b64_tr_b16 v[214:215], v186 offset:38400
	s_mov_b32 s77, s76
	s_mov_b32 s78, s76
	s_mov_b32 s79, s76
	v_mov_b64_e32 v[12:13], s[76:77]
	v_mov_b64_e32 v[14:15], s[78:79]
	v_mfma_f32_32x32x16_bf16 v[98:113], v[208:211], v[122:125], v[98:113]
	v_exp_f32_e32 v82, v82
	v_exp_f32_e32 v83, v83
	v_exp_f32_e32 v84, v84
	v_mfma_f32_32x32x16_bf16 v[98:113], v[216:219], v[126:129], v[98:113]
	v_exp_f32_e32 v85, v85
	v_exp_f32_e32 v86, v86
	v_exp_f32_e32 v87, v87
	v_mfma_f32_32x32x16_bf16 v[98:113], v[224:227], v[130:133], v[98:113]
	v_exp_f32_e32 v88, v88
	v_exp_f32_e32 v89, v89
	ds_read_b64_tr_b16 v[220:221], v186 offset:34816
	ds_read_b64_tr_b16 v[222:223], v186 offset:35328
	ds_read_b64_tr_b16 v[192:193], v186 offset:38912
	ds_read_b64_tr_b16 v[194:195], v186 offset:39424
	ds_read_b64_tr_b16 v[200:201], v186 offset:35840
	ds_read_b64_tr_b16 v[202:203], v186 offset:36352
	ds_read_b64_tr_b16 v[208:209], v186 offset:39936
	ds_read_b64_tr_b16 v[210:211], v186 offset:40448
	v_cvt_pk_bf16_f32 v228, v82, v83
	v_cvt_pk_bf16_f32 v229, v84, v85
	v_cvt_pk_bf16_f32 v230, v86, v87
	v_cvt_pk_bf16_f32 v231, v88, v89
	s_waitcnt lgkmcnt(8)
	s_nop 0
	v_mfma_f32_32x32x16_bf16 v[34:49], v[188:191], v[228:231], v[34:49]
	v_exp_f32_e32 v90, v90
	v_exp_f32_e32 v91, v91
	v_exp_f32_e32 v92, v92
	v_mfma_f32_32x32x16_bf16 v[18:33], v[196:199], v[228:231], v[18:33]
	v_exp_f32_e32 v93, v93
	v_exp_f32_e32 v94, v94
	v_exp_f32_e32 v95, v95
	v_mfma_f32_32x32x16_bf16 v[66:81], v[12:15], v[228:231], v[66:81]
	v_exp_f32_e32 v96, v96
	v_exp_f32_e32 v97, v97
	v_cvt_pk_bf16_f32 v232, v90, v91
	v_cvt_pk_bf16_f32 v233, v92, v93
	v_cvt_pk_bf16_f32 v234, v94, v95
	v_cvt_pk_bf16_f32 v235, v96, v97
	v_exp_f32_e32 v98, v98
	v_exp_f32_e32 v99, v99
	v_mfma_f32_32x32x16_bf16 v[34:49], v[204:207], v[232:235], v[34:49]
	v_exp_f32_e32 v100, v100
	v_exp_f32_e32 v101, v101
	v_exp_f32_e32 v102, v102
	v_mfma_f32_32x32x16_bf16 v[18:33], v[212:215], v[232:235], v[18:33]
	v_exp_f32_e32 v103, v103
	v_exp_f32_e32 v104, v104
	v_exp_f32_e32 v105, v105
	v_mfma_f32_32x32x16_bf16 v[66:81], v[12:15], v[232:235], v[66:81]
	v_cvt_pk_bf16_f32 v236, v98, v99
	v_cvt_pk_bf16_f32 v237, v100, v101
	v_cvt_pk_bf16_f32 v238, v102, v103
	v_cvt_pk_bf16_f32 v239, v104, v105
	v_exp_f32_e32 v106, v106
	v_exp_f32_e32 v107, v107
	s_waitcnt lgkmcnt(0)
	v_mfma_f32_32x32x16_bf16 v[34:49], v[220:223], v[236:239], v[34:49]
	v_exp_f32_e32 v108, v108
	v_exp_f32_e32 v109, v109
	v_exp_f32_e32 v110, v110
	v_mfma_f32_32x32x16_bf16 v[18:33], v[192:195], v[236:239], v[18:33]
	v_exp_f32_e32 v111, v111
	v_exp_f32_e32 v112, v112
	v_exp_f32_e32 v113, v113
	v_mfma_f32_32x32x16_bf16 v[66:81], v[12:15], v[236:239], v[66:81]
	v_cvt_pk_bf16_f32 v240, v106, v107
	v_cvt_pk_bf16_f32 v241, v108, v109
	v_cvt_pk_bf16_f32 v242, v110, v111
	v_cvt_pk_bf16_f32 v243, v112, v113
	s_nop 1
	v_mfma_f32_32x32x16_bf16 v[34:49], v[200:203], v[240:243], v[34:49]
	v_mfma_f32_32x32x16_bf16 v[18:33], v[208:211], v[240:243], v[18:33]
	v_mfma_f32_32x32x16_bf16 v[66:81], v[12:15], v[240:243], v[66:81]
	s_branch .LBB0_431
